# baseline (speedup 1.0000x reference)
; __device__ __forceinline__ float bflo(unsigned w) { return __uint_as_float(w << 16); }
; __device__ __forceinline__ float bfhi(unsigned w) { return __uint_as_float(w & 0xffff0000u); }
; __device__ __forceinline__ float wave_sum(float x) { x = row16_sum(x); return (rdl(x, 0) + rdl(x, 16)) + (rdl(x, 32) + rdl(x, 48)); }
; __device__ __forceinline__ void phase_convert_x(const Params& p) {
;     ...
;   for (int row = wave; row < M_TOK; row += nw) {
;     const float* src = row < 16384 ? p.x_prompt + (size_t)row * DM : p.x_sample + (size_t)(row - 16384) * DM;
;     float ss = 0.f;
; #pragma unroll
;     for (int it = 0; it < 8; ++it) {
;       int c = (it * 64 + lane) * 4;
;       float4 v = *(const float4*)(src + c);
;       unsigned p0 = pack2(v.x, v.y), p1 = pack2(v.z, v.w);
;       float a = bflo(p0), b = bfhi(p0), cc = bflo(p1), d = bfhi(p1);
;       ss += a * a + b * b + cc * cc + d * d;
;       *(uint2*)(xb + (size_t)row * DM + c) = make_uint2(p0, p1);
;     }
;     ss = wave_sum(ss);
;     if (lane == 0) rstd[row] = rsqrtf(ss * (1.0f / DM) + 1e-6f);
;   }
.LBB0_6:
	v_cmp_lt_i32_e64 s[0:1], s33, v2
	v_mov_b64_e32 v[20:21], v[2:3]
	v_mov_b64_e32 v[22:23], v[8:9]
	s_and_saveexec_b64 s[52:53], s[0:1]
	v_add_u32_e32 v4, 0xffffc000, v2
	v_lshlrev_b64 v[20:21], 13, v[4:5]
	v_mov_b32_e32 v4, v2
	v_lshl_add_u64 v[22:23], s[54:55], 0, v[20:21]
	v_mov_b64_e32 v[20:21], v[4:5]
	s_or_b64 exec, exec, s[52:53]
	v_lshl_add_u64 v[28:29], v[22:23], 0, v[10:11]
	global_load_dwordx4 v[44:47], v[28:29], off
	global_load_dwordx4 v[48:51], v[28:29], off offset:1024
	global_load_dwordx4 v[52:55], v[28:29], off offset:2048
	global_load_dwordx4 v[56:59], v[28:29], off offset:3072
	v_lshl_add_u64 v[76:77], v[22:23], 0, v[12:13]
	global_load_dwordx4 v[60:63], v[76:77], off
	v_lshl_add_u64 v[76:77], v[22:23], 0, v[14:15]
	global_load_dwordx4 v[64:67], v[76:77], off
	v_lshl_add_u64 v[76:77], v[22:23], 0, v[16:17]
	global_load_dwordx4 v[68:71], v[76:77], off
	v_lshl_add_u64 v[22:23], v[22:23], 0, v[18:19]
	global_load_dwordx4 v[72:75], v[22:23], off
	v_lshlrev_b64 v[30:31], 12, v[20:21]
	v_lshl_add_u64 v[30:31], v[6:7], 0, v[30:31]
	s_waitcnt vmcnt(7)
	v_cvt_pk_bf16_f32 v32, v44, v45
	v_cvt_pk_bf16_f32 v33, v46, v47
	global_store_dwordx2 v[30:31], v[32:33], off
	v_lshlrev_b32_e32 v4, 16, v32
	s_waitcnt vmcnt(7)
	v_cvt_pk_bf16_f32 v34, v48, v49
	v_cvt_pk_bf16_f32 v35, v50, v51
	global_store_dwordx2 v[30:31], v[34:35], off offset:512
	s_waitcnt vmcnt(7)
	v_cvt_pk_bf16_f32 v36, v52, v53
	v_cvt_pk_bf16_f32 v37, v54, v55
	global_store_dwordx2 v[30:31], v[36:37], off offset:1024
	s_waitcnt vmcnt(7)
	v_cvt_pk_bf16_f32 v38, v56, v57
	v_cvt_pk_bf16_f32 v39, v58, v59
	global_store_dwordx2 v[30:31], v[38:39], off offset:1536
	s_waitcnt vmcnt(7)
	v_cvt_pk_bf16_f32 v40, v60, v61
	v_cvt_pk_bf16_f32 v41, v62, v63
	global_store_dwordx2 v[30:31], v[40:41], off offset:2048
	s_waitcnt vmcnt(7)
	v_cvt_pk_bf16_f32 v42, v64, v65
	v_cvt_pk_bf16_f32 v43, v66, v67
	global_store_dwordx2 v[30:31], v[42:43], off offset:2560
	s_waitcnt vmcnt(7)
	v_cvt_pk_bf16_f32 v28, v68, v69
	v_cvt_pk_bf16_f32 v29, v70, v71
	global_store_dwordx2 v[30:31], v[28:29], off offset:3072
	v_and_b32_e32 v26, 0xffff0000, v32
	v_mul_f32_e32 v26, v26, v26
	v_lshlrev_b32_e32 v27, 16, v33
	v_fmac_f32_e32 v26, v4, v4
	v_fmac_f32_e32 v26, v27, v27
	v_and_b32_e32 v27, 0xffff0000, v34
	v_and_b32_e32 v32, 0xffff0000, v33
	v_lshlrev_b32_e32 v4, 16, v34
	v_mul_f32_e32 v27, v27, v27
	v_fmac_f32_e32 v26, v32, v32
	v_lshlrev_b32_e32 v32, 16, v35
	v_fmac_f32_e32 v27, v4, v4
	v_and_b32_e32 v33, 0xffff0000, v35
	v_fmac_f32_e32 v27, v32, v32
	v_fmac_f32_e32 v27, v33, v33
	v_add_f32_e32 v4, v26, v27
	v_and_b32_e32 v27, 0xffff0000, v36
	v_lshlrev_b32_e32 v26, 16, v36
	v_mul_f32_e32 v27, v27, v27
	v_lshlrev_b32_e32 v32, 16, v37
	v_fmac_f32_e32 v27, v26, v26
	v_and_b32_e32 v33, 0xffff0000, v37
	v_fmac_f32_e32 v27, v32, v32
	v_fmac_f32_e32 v27, v33, v33
	v_add_f32_e32 v4, v4, v27
	v_and_b32_e32 v27, 0xffff0000, v38
	v_lshlrev_b32_e32 v26, 16, v38
	v_mul_f32_e32 v27, v27, v27
	v_lshlrev_b32_e32 v32, 16, v39
	v_fmac_f32_e32 v27, v26, v26
	v_and_b32_e32 v33, 0xffff0000, v39
	v_fmac_f32_e32 v27, v32, v32
	v_fmac_f32_e32 v27, v33, v33
	v_add_f32_e32 v4, v4, v27
	v_and_b32_e32 v27, 0xffff0000, v40
	v_lshlrev_b32_e32 v26, 16, v40
	v_mul_f32_e32 v27, v27, v27
	v_lshlrev_b32_e32 v32, 16, v41
	v_fmac_f32_e32 v27, v26, v26
	v_and_b32_e32 v33, 0xffff0000, v41
	v_fmac_f32_e32 v27, v32, v32
	v_fmac_f32_e32 v27, v33, v33
	v_add_f32_e32 v4, v4, v27
	v_and_b32_e32 v27, 0xffff0000, v42
	v_lshlrev_b32_e32 v26, 16, v42
	v_mul_f32_e32 v27, v27, v27
	v_lshlrev_b32_e32 v32, 16, v43
	v_fmac_f32_e32 v27, v26, v26
	v_and_b32_e32 v33, 0xffff0000, v43
	v_fmac_f32_e32 v27, v32, v32
	v_fmac_f32_e32 v27, v33, v33
	v_add_f32_e32 v4, v4, v27
	v_and_b32_e32 v27, 0xffff0000, v28
	v_lshlrev_b32_e32 v26, 16, v28
	v_mul_f32_e32 v27, v27, v27
	v_lshlrev_b32_e32 v28, 16, v29
	v_fmac_f32_e32 v27, v26, v26
	v_and_b32_e32 v29, 0xffff0000, v29
	v_fmac_f32_e32 v27, v28, v28
	v_fmac_f32_e32 v27, v29, v29
	v_add_f32_e32 v4, v4, v27
	s_waitcnt vmcnt(7)
	v_cvt_pk_bf16_f32 v22, v72, v73
	v_cvt_pk_bf16_f32 v23, v74, v75
	v_and_b32_e32 v25, 0xffff0000, v22
	v_lshlrev_b32_e32 v24, 16, v22
	global_store_dwordx2 v[30:31], v[22:23], off offset:3584
	v_mul_f32_e32 v22, v25, v25
	v_lshlrev_b32_e32 v26, 16, v23
	v_fmac_f32_e32 v22, v24, v24
	v_and_b32_e32 v27, 0xffff0000, v23
	v_fmac_f32_e32 v22, v26, v26
	v_fmac_f32_e32 v22, v27, v27
	v_add_f32_e32 v4, v4, v22
	s_nop 1
	v_add_f32_dpp v4, v4, v4 quad_perm:[1,0,3,2] row_mask:0xf bank_mask:0xf bound_ctrl:1
	s_nop 1
	v_add_f32_dpp v4, v4, v4 quad_perm:[2,3,0,1] row_mask:0xf bank_mask:0xf bound_ctrl:1
	s_nop 1
	v_add_f32_dpp v4, v4, v4 row_half_mirror row_mask:0xf bank_mask:0xf bound_ctrl:1
	s_nop 1
	v_add_f32_dpp v4, v4, v4 row_mirror row_mask:0xf bank_mask:0xf bound_ctrl:1
	s_nop 0
	v_readlane_b32 s0, v4, 0
	v_readlane_b32 s81, v4, 16
	v_readlane_b32 s1, v4, 32
	v_readlane_b32 s82, v4, 48
	s_and_saveexec_b64 s[52:53], vcc
	s_cbranch_execz .LBB0_5
	v_mov_b32_e32 v22, s81
	v_mov_b32_e32 v23, s82
	v_pk_add_f32 v[22:23], s[0:1], v[22:23]
	v_lshl_add_u64 v[20:21], v[20:21], 2, s[6:7]
	v_add_f32_e32 v4, v22, v23
	v_fmamk_f32 v4, v4, 0x3a000000, v1
	v_mul_f32_e32 v22, 0x4b800000, v4
	v_cmp_gt_f32_e64 s[0:1], s77, v4
	s_nop 1
	v_cndmask_b32_e64 v4, v4, v22, s[0:1]
	v_rsq_f32_e32 v4, v4
	s_nop 0
	v_mul_f32_e32 v22, 0x45800000, v4
	v_cndmask_b32_e64 v4, v4, v22, s[0:1]
	global_store_dword v[20:21], v4, off
	s_branch .LBB0_5

; __device__ __forceinline__ float bflo(unsigned w) { return __uint_as_float(w << 16); }
; __device__ __forceinline__ float bfhi(unsigned w) { return __uint_as_float(w & 0xffff0000u); }
; __device__ __forceinline__ int opaque_tid() { int t; asm volatile("v_mov_b32 %0, %1" : "=v"(t) : "v"((int)threadIdx.x)); return t; }
; __device__ __forceinline__ float wave_sum(float x) { x = row16_sum(x); return (rdl(x, 0) + rdl(x, 16)) + (rdl(x, 32) + rdl(x, 48)); }
; __device__ __forceinline__ void phase_final(const Params& p) {
;   const int tidx = opaque_tid();
;   const int lane = tidx & 63;
;   const int wave = blockIdx.x * 8 + (tidx >> 6), nw = gridDim.x * 8;
;   const u16* xb = (const u16*)(p.ws + OFF_XB);
;   for (int row = wave; row < M_TOK; row += nw) {
;     float x[32];
;     float ss = 0.f;
; #pragma unroll
;     for (int it = 0; it < 4; ++it) {
;       int c = (it * 64 + lane) * 8;
;       uint4 v = *(const uint4*)(xb + (size_t)row * DM + c);
;       x[it * 8 + 0] = bflo(v.x); x[it * 8 + 1] = bfhi(v.x);
;       x[it * 8 + 2] = bflo(v.y); x[it * 8 + 3] = bfhi(v.y);
;       x[it * 8 + 4] = bflo(v.z); x[it * 8 + 5] = bfhi(v.z);
;       x[it * 8 + 6] = bflo(v.w); x[it * 8 + 7] = bfhi(v.w);
; #pragma unroll
;       for (int j = 0; j < 8; ++j) ss += x[it * 8 + j] * x[it * 8 + j];
;     }
;     ss = wave_sum(ss);
;     float rs = rsqrtf(ss * (1.0f / DM) + 1e-6f);
; #pragma unroll
;     for (int it = 0; it < 4; ++it) {
;       int c = (it * 64 + lane) * 8;
;       float4 g0 = *(const float4*)(p.final_norm + c), g1 = *(const float4*)(p.final_norm + c + 4);
.LBB0_1752:
	s_cmp_lt_i32 s78, 14
	s_cselect_b64 s[0:1], -1, 0
	s_cmp_gt_i32 s79, 13
	s_cselect_b64 s[4:5], -1, 0
	s_and_b64 s[0:1], s[0:1], s[4:5]
	s_andn2_b64 vcc, exec, s[0:1]
	s_cbranch_vccnz .LBB0_1764
	s_waitcnt vmcnt(25)
	v_mov_b32 v8, v146
	s_mov_b32 s0, 0xc000
	s_waitcnt vmcnt(2)
	v_ashrrev_i32_e32 v0, 6, v8
	v_lshl_add_u32 v0, s2, 3, v0
	v_cmp_gt_i32_e32 vcc, s0, v0
	s_and_saveexec_b64 s[0:1], vcc
	s_cbranch_execz .LBB0_1756
	v_lshlrev_b32_e32 v1, 5, v8
	s_waitcnt vmcnt(0)
	v_and_b32_e32 v6, 0x7e0, v1
	v_ashrrev_i32_e32 v1, 31, v0
	v_lshlrev_b64 v[10:11], 12, v[0:1]
	v_and_b32_e32 v12, 63, v8
	v_lshl_or_b32 v10, v12, 4, v10
	v_lshl_add_u64 v[8:9], s[74:75], 0, v[10:11]
	v_lshlrev_b64 v[10:11], 13, v[0:1]
	s_lshl_b32 s2, s76, 3
	v_mov_b32_e32 v7, 0
	v_lshl_or_b32 v10, v12, 5, v10
	v_lshl_add_u64 v[2:3], s[70:71], 0, v[6:7]
	v_or_b32_e32 v4, 0x1000, v6
	v_mov_b32_e32 v5, v7
	v_or_b32_e32 v6, 0x1800, v6
	s_mov_b64 s[4:5], 0x800
	s_ashr_i32 s3, s2, 31
	v_lshl_add_u64 v[10:11], s[72:73], 0, v[10:11]
	s_mov_b64 s[6:7], 0x1000
	v_lshl_add_u64 v[4:5], s[70:71], 0, v[4:5]
	v_lshl_add_u64 v[6:7], s[70:71], 0, v[6:7]
	v_lshl_add_u64 v[8:9], v[8:9], 0, s[4:5]
	s_lshl_b64 s[4:5], s[2:3], 12
	v_lshl_add_u64 v[10:11], v[10:11], 0, s[6:7]
	s_lshl_b64 s[6:7], s[2:3], 13
	s_mov_b64 s[8:9], 0
	v_mov_b32_e32 v1, 0x358637bd
	s_mov_b32 s3, 0x800000
	s_mov_b32 s10, 0xbfff
	global_load_dwordx4 v[100:103], v[2:3], off offset:2048
	global_load_dwordx4 v[104:107], v[2:3], off offset:2064
	global_load_dwordx4 v[108:111], v[4:5], off
	global_load_dwordx4 v[112:115], v[4:5], off offset:16
	global_load_dwordx4 v[116:119], v[6:7], off
	global_load_dwordx4 v[120:123], v[6:7], off offset:16
	s_waitcnt vmcnt(0)
; __device__ __forceinline__ float bflo(unsigned w) { return __uint_as_float(w << 16); }
; __device__ __forceinline__ float bfhi(unsigned w) { return __uint_as_float(w & 0xffff0000u); }
; __device__ __forceinline__ float wave_sum(float x) { x = row16_sum(x); return (rdl(x, 0) + rdl(x, 16)) + (rdl(x, 32) + rdl(x, 48)); }
; __device__ __forceinline__ void phase_final(const Params& p) {
;     ...
;   for (int row = wave; row < M_TOK; row += nw) {
;     float x[32];
;     float ss = 0.f;
; #pragma unroll
;     for (int it = 0; it < 4; ++it) {
;       int c = (it * 64 + lane) * 8;
;       uint4 v = *(const uint4*)(xb + (size_t)row * DM + c);
;       x[it * 8 + 0] = bflo(v.x); x[it * 8 + 1] = bfhi(v.x);
;       x[it * 8 + 2] = bflo(v.y); x[it * 8 + 3] = bfhi(v.y);
;       x[it * 8 + 4] = bflo(v.z); x[it * 8 + 5] = bfhi(v.z);
;       x[it * 8 + 6] = bflo(v.w); x[it * 8 + 7] = bfhi(v.w);
; #pragma unroll
;       for (int j = 0; j < 8; ++j) ss += x[it * 8 + j] * x[it * 8 + j];
;     }
;     ss = wave_sum(ss);
;     float rs = rsqrtf(ss * (1.0f / DM) + 1e-6f);
; #pragma unroll
;     for (int it = 0; it < 4; ++it) {
;       int c = (it * 64 + lane) * 8;
;       float4 g0 = *(const float4*)(p.final_norm + c), g1 = *(const float4*)(p.final_norm + c + 4);
;       float4 o0, o1;
;       o0.x = x[it * 8 + 0] * rs * g0.x; o0.y = x[it * 8 + 1] * rs * g0.y;
;       o0.z = x[it * 8 + 2] * rs * g0.z; o0.w = x[it * 8 + 3] * rs * g0.w;
;       o1.x = x[it * 8 + 4] * rs * g1.x; o1.y = x[it * 8 + 5] * rs * g1.y;
;       o1.z = x[it * 8 + 6] * rs * g1.z; o1.w = x[it * 8 + 7] * rs * g1.w;
;       *(float4*)(p.out + (size_t)row * DM + c) = o0;
;       *(float4*)(p.out + (size_t)row * DM + c + 4) = o1;
;     }
.LBB0_1755:
	global_load_dwordx4 v[12:15], v[8:9], off offset:-2048
	global_load_dwordx4 v[16:19], v[8:9], off offset:-1024
	global_load_dwordx4 v[20:23], v[8:9], off
	global_load_dwordx4 v[24:27], v[8:9], off offset:1024
	global_load_dwordx4 v[28:31], v[2:3], off offset:16
	global_load_dwordx4 v[32:35], v[2:3], off
	v_add_u32_e32 v0, s2, v0
	v_lshl_add_u64 v[8:9], v[8:9], 0, s[4:5]
	s_waitcnt vmcnt(5)
	v_lshlrev_b32_e32 v36, 16, v12
	v_and_b32_e32 v37, 0xffff0000, v12
	v_lshlrev_b32_e32 v12, 16, v13
	v_and_b32_e32 v13, 0xffff0000, v13
	s_waitcnt vmcnt(4)
	v_lshlrev_b32_e32 v40, 16, v16
	v_and_b32_e32 v41, 0xffff0000, v16
	v_lshlrev_b32_e32 v42, 16, v17
	v_and_b32_e32 v43, 0xffff0000, v17
	v_pk_mul_f32 v[16:17], v[36:37], v[36:37]
	v_lshlrev_b32_e32 v44, 16, v18
	v_and_b32_e32 v45, 0xffff0000, v18
	v_lshlrev_b32_e32 v46, 16, v19
	v_and_b32_e32 v47, 0xffff0000, v19
	v_pk_mul_f32 v[18:19], v[12:13], v[12:13]
	v_add_f32_e32 v16, v16, v17
	v_lshlrev_b32_e32 v38, 16, v14
	v_and_b32_e32 v39, 0xffff0000, v14
	v_add_f32_e32 v16, v16, v18
	v_pk_mul_f32 v[56:57], v[38:39], v[38:39]
	v_add_f32_e32 v16, v19, v16
	v_lshlrev_b32_e32 v14, 16, v15
	v_and_b32_e32 v15, 0xffff0000, v15
	v_add_f32_e32 v16, v56, v16
	v_pk_mul_f32 v[58:59], v[14:15], v[14:15]
	v_add_f32_e32 v16, v57, v16
	v_add_f32_e32 v16, v58, v16
	v_pk_mul_f32 v[60:61], v[40:41], v[40:41]
	v_add_f32_e32 v16, v59, v16
	v_add_f32_e32 v16, v60, v16
	v_pk_mul_f32 v[62:63], v[42:43], v[42:43]
	v_add_f32_e32 v16, v61, v16
	v_add_f32_e32 v16, v62, v16
	v_pk_mul_f32 v[64:65], v[44:45], v[44:45]
	v_add_f32_e32 v16, v63, v16
	v_add_f32_e32 v16, v64, v16
	v_pk_mul_f32 v[66:67], v[46:47], v[46:47]
	v_add_f32_e32 v16, v65, v16
	s_waitcnt vmcnt(3)
	v_lshlrev_b32_e32 v48, 16, v20
	v_and_b32_e32 v49, 0xffff0000, v20
	v_add_f32_e32 v16, v66, v16
	v_pk_mul_f32 v[68:69], v[48:49], v[48:49]
	v_add_f32_e32 v16, v67, v16
	v_lshlrev_b32_e32 v20, 16, v21
	v_and_b32_e32 v21, 0xffff0000, v21
	v_add_f32_e32 v16, v68, v16
	v_pk_mul_f32 v[70:71], v[20:21], v[20:21]
	v_add_f32_e32 v16, v69, v16
	v_lshlrev_b32_e32 v50, 16, v22
	v_and_b32_e32 v51, 0xffff0000, v22
	v_add_f32_e32 v16, v70, v16
	v_pk_mul_f32 v[72:73], v[50:51], v[50:51]
	v_add_f32_e32 v16, v71, v16
	v_lshlrev_b32_e32 v22, 16, v23
	v_and_b32_e32 v23, 0xffff0000, v23
	v_add_f32_e32 v16, v72, v16
	v_pk_mul_f32 v[74:75], v[22:23], v[22:23]
	v_add_f32_e32 v16, v73, v16
	s_waitcnt vmcnt(2)
	v_lshlrev_b32_e32 v52, 16, v24
	v_and_b32_e32 v53, 0xffff0000, v24
	v_add_f32_e32 v16, v74, v16
	v_pk_mul_f32 v[76:77], v[52:53], v[52:53]
	v_add_f32_e32 v16, v75, v16
	v_lshlrev_b32_e32 v24, 16, v25
	v_and_b32_e32 v25, 0xffff0000, v25
	v_add_f32_e32 v16, v76, v16
	v_pk_mul_f32 v[78:79], v[24:25], v[24:25]
	v_add_f32_e32 v16, v77, v16
	v_lshlrev_b32_e32 v54, 16, v26
	v_and_b32_e32 v55, 0xffff0000, v26
	v_add_f32_e32 v16, v78, v16
	v_pk_mul_f32 v[80:81], v[54:55], v[54:55]
	v_add_f32_e32 v16, v79, v16
	v_lshlrev_b32_e32 v26, 16, v27
	v_and_b32_e32 v27, 0xffff0000, v27
	v_add_f32_e32 v16, v80, v16
	v_pk_mul_f32 v[82:83], v[26:27], v[26:27]
	v_add_f32_e32 v16, v81, v16
	v_add_f32_e32 v16, v82, v16
	v_add_f32_e32 v16, v83, v16
	s_nop 1
	v_add_f32_dpp v16, v16, v16 quad_perm:[1,0,3,2] row_mask:0xf bank_mask:0xf bound_ctrl:1
	s_nop 1
	v_add_f32_dpp v16, v16, v16 quad_perm:[2,3,0,1] row_mask:0xf bank_mask:0xf bound_ctrl:1
	s_nop 1
	v_add_f32_dpp v16, v16, v16 row_half_mirror row_mask:0xf bank_mask:0xf bound_ctrl:1
	s_nop 1
	v_add_f32_dpp v16, v16, v16 row_mirror row_mask:0xf bank_mask:0xf bound_ctrl:1
	s_nop 0
	v_readlane_b32 s11, v16, 16
	v_readlane_b32 s14, v16, 48
	v_readlane_b32 s12, v16, 0
	v_readlane_b32 s13, v16, 32
	v_mov_b32_e32 v16, s11
	v_mov_b32_e32 v17, s14
	v_pk_add_f32 v[16:17], s[12:13], v[16:17]
	s_nop 0
	v_add_f32_e32 v16, v16, v17
	v_fmamk_f32 v16, v16, 0x3a000000, v1
	v_mul_f32_e32 v17, 0x4b800000, v16
	v_cmp_gt_f32_e32 vcc, s3, v16
	s_nop 1
	v_cndmask_b32_e32 v16, v16, v17, vcc
	v_rsq_f32_e32 v16, v16
	s_nop 0
	v_mul_f32_e32 v17, 0x45800000, v16
	v_cndmask_b32_e32 v56, v16, v17, vcc
	v_pk_mul_f32 v[16:17], v[56:57], v[36:37] op_sel_hi:[0,1]
	v_pk_mul_f32 v[18:19], v[56:57], v[12:13] op_sel_hi:[0,1]
	v_pk_mul_f32 v[36:37], v[56:57], v[38:39] op_sel_hi:[0,1]
	v_pk_mul_f32 v[38:39], v[56:57], v[14:15] op_sel_hi:[0,1]
	s_waitcnt vmcnt(0)
	v_pk_mul_f32 v[12:13], v[32:33], v[16:17]
	v_pk_mul_f32 v[14:15], v[34:35], v[18:19]
	v_pk_mul_f32 v[16:17], v[28:29], v[36:37]
	v_pk_mul_f32 v[18:19], v[30:31], v[38:39]
	global_store_dwordx4 v[10:11], v[12:15], off offset:-4096
	global_store_dwordx4 v[10:11], v[16:19], off offset:-4080
	v_pk_mul_f32 v[28:29], v[56:57], v[40:41] op_sel_hi:[0,1]
	v_pk_mul_f32 v[30:31], v[56:57], v[42:43] op_sel_hi:[0,1]
	v_pk_mul_f32 v[32:33], v[56:57], v[44:45] op_sel_hi:[0,1]
	v_pk_mul_f32 v[34:35], v[56:57], v[46:47] op_sel_hi:[0,1]
	v_pk_mul_f32 v[20:21], v[56:57], v[20:21] op_sel_hi:[0,1]
	v_pk_mul_f32 v[22:23], v[56:57], v[22:23] op_sel_hi:[0,1]
	v_cmp_lt_i32_e32 vcc, s10, v0
	v_pk_mul_f32 v[26:27], v[56:57], v[26:27] op_sel_hi:[0,1]
	s_or_b64 s[8:9], vcc, s[8:9]
	v_pk_mul_f32 v[12:13], v[28:29], v[100:101]
	v_pk_mul_f32 v[14:15], v[30:31], v[102:103]
	v_pk_mul_f32 v[16:17], v[32:33], v[104:105]
	v_pk_mul_f32 v[18:19], v[34:35], v[106:107]
	global_store_dwordx4 v[10:11], v[12:15], off offset:-2048
	global_store_dwordx4 v[10:11], v[16:19], off offset:-2032
	v_pk_mul_f32 v[28:29], v[56:57], v[48:49] op_sel_hi:[0,1]
	v_pk_mul_f32 v[30:31], v[56:57], v[50:51] op_sel_hi:[0,1]
	v_pk_mul_f32 v[12:13], v[28:29], v[108:109]
	v_pk_mul_f32 v[14:15], v[20:21], v[110:111]
	v_pk_mul_f32 v[16:17], v[30:31], v[112:113]
	v_pk_mul_f32 v[18:19], v[22:23], v[114:115]
	global_store_dwordx4 v[10:11], v[12:15], off
	global_store_dwordx4 v[10:11], v[16:19], off offset:16
	v_pk_mul_f32 v[20:21], v[56:57], v[52:53] op_sel_hi:[0,1]
	v_pk_mul_f32 v[22:23], v[56:57], v[24:25] op_sel_hi:[0,1]
	v_pk_mul_f32 v[24:25], v[56:57], v[54:55] op_sel_hi:[0,1]
	v_pk_mul_f32 v[12:13], v[20:21], v[116:117]
	v_pk_mul_f32 v[14:15], v[22:23], v[118:119]
	v_pk_mul_f32 v[16:17], v[24:25], v[120:121]
	v_pk_mul_f32 v[18:19], v[26:27], v[122:123]
	global_store_dwordx4 v[10:11], v[12:15], off offset:2048
	global_store_dwordx4 v[10:11], v[16:19], off offset:2064
	v_lshl_add_u64 v[10:11], v[10:11], 0, s[6:7]
	s_andn2_b64 exec, exec, s[8:9]
	s_cbranch_execnz .LBB0_1755
